# REC_SPLIT retuned 12288 -> 10240 tokens (less rec-norm in P1a's filler, more in the combine phase), on v19
# speedup vs baseline: 1.0030x; 1.0002x over previous
.LBB0_464:
	s_cmpk_lt_i32 s74, 0x80
	s_cselect_b64 s[0:1], -1, 0
	s_xor_b64 s[4:5], s[92:93], -1
	s_or_b64 s[0:1], s[0:1], s[4:5]
	s_and_b64 vcc, exec, s[0:1]
	s_cbranch_vccnz .LBB0_469
	s_lshl_b32 s0, s74, 9
	v_add_u32_e32 v5, s0, v171
	v_add_u32_e32 v0, 0xffff0000, v5
	s_mov_b32 s0, 0x140000
	v_cmp_gt_i32_e32 vcc, s0, v0
	s_and_saveexec_b64 s[0:1], vcc
	v_readlane_b32 s8, v246, 4
	v_readlane_b32 s18, v246, 14
	v_readlane_b32 s19, v246, 15
	v_readlane_b32 s9, v246, 5
	v_readlane_b32 s10, v246, 6
	v_readlane_b32 s11, v246, 7
	v_readlane_b32 s12, v246, 8
	v_readlane_b32 s13, v246, 9
	v_readlane_b32 s14, v246, 10
	v_readlane_b32 s15, v246, 11
	v_readlane_b32 s16, v246, 12
	v_readlane_b32 s17, v246, 13
	v_readlane_b32 s20, v246, 16
	v_readlane_b32 s21, v246, 17
	v_readlane_b32 s22, v246, 18
	v_readlane_b32 s23, v246, 19
	s_cbranch_execz .LBB0_468
	v_mbcnt_lo_u32_b32 v0, -1, 0
	v_mbcnt_hi_u32_b32 v3, -1, v0
	v_and_b32_e32 v1, 64, v3
	v_xor_b32_e32 v0, 1, v3
	v_add_u32_e32 v4, 64, v1
	v_cmp_lt_i32_e32 vcc, v0, v4
	v_xor_b32_e32 v1, 2, v3
	v_xor_b32_e32 v2, 4, v3
	v_cndmask_b32_e32 v0, v3, v0, vcc
	v_cmp_lt_i32_e32 vcc, v1, v4
	v_xor_b32_e32 v6, 8, v3
	s_add_u32 s4, s76, 0xe000000
	v_cndmask_b32_e32 v1, v3, v1, vcc
	v_cmp_lt_i32_e32 vcc, v2, v4
	s_addc_u32 s5, s77, 0
	v_lshlrev_b32_e32 v0, 2, v0
	v_cndmask_b32_e32 v2, v3, v2, vcc
	v_cmp_lt_i32_e32 vcc, v6, v4
	v_lshlrev_b32_e32 v1, 2, v1
	v_lshlrev_b32_e32 v2, 2, v2
	v_cndmask_b32_e32 v3, v3, v6, vcc
	v_mov_b32_e32 v6, 0xfff80000
	v_lshlrev_b32_e32 v3, 2, v3
	v_add_u32_e32 v4, 0xfffe0000, v5
	v_lshl_add_u32 v5, v5, 3, v6
	s_mov_b64 s[6:7], 0
	v_mov_b32_e32 v6, 0x358637bd
	s_mov_b32 s8, 0x12ffff

.LBB0_584:
	s_or_b64 exec, exec, s[0:1]
	s_and_b64 s[0:1], s[92:93], exec
	s_cselect_b32 s0, 0x140000, 0
	v_add_u32_e32 v0, s0, v6
	s_mov_b32 s0, 0x200000
	v_cmp_gt_i32_e32 vcc, s0, v0
	s_and_saveexec_b64 s[0:1], vcc
	s_cbranch_execz .LBB0_587
	v_mbcnt_lo_u32_b32 v1, -1, 0
	v_mbcnt_hi_u32_b32 v4, -1, v1
	v_and_b32_e32 v2, 64, v4
	v_xor_b32_e32 v1, 1, v4
	v_add_u32_e32 v5, 64, v2
	v_cmp_lt_i32_e32 vcc, v1, v5
	v_xor_b32_e32 v2, 2, v4
	v_xor_b32_e32 v3, 4, v4
	v_cndmask_b32_e32 v1, v4, v1, vcc
	v_cmp_lt_i32_e32 vcc, v2, v5
	v_xor_b32_e32 v6, 8, v4
	v_readlane_b32 s6, v246, 48
	v_cndmask_b32_e32 v2, v4, v2, vcc
	v_cmp_lt_i32_e32 vcc, v3, v5
	s_add_u32 s4, s76, 0xe000000
	v_readlane_b32 s7, v246, 49
	v_cndmask_b32_e32 v3, v4, v3, vcc
	v_cmp_lt_i32_e32 vcc, v6, v5
	s_addc_u32 s5, s77, 0
	v_lshlrev_b32_e32 v1, 2, v1
	v_cndmask_b32_e32 v4, v4, v6, vcc
	v_lshlrev_b32_e32 v2, 2, v2
	v_lshlrev_b32_e32 v3, 2, v3
	v_lshlrev_b32_e32 v4, 2, v4
	v_lshlrev_b32_e32 v5, 3, v0
	s_lshl_b32 s9, s6, 12
	s_mov_b64 s[6:7], 0
	v_mov_b32_e32 v6, 0x358637bd
	s_mov_b32 s10, 0x1fffff
